# GEMM1/FF1 unit-loop header: next unit (pm, pn) in closed form for the fixed shapes instead of the division chain
# speedup vs baseline: 1.0030x; 1.0030x over previous
.LBB0_221:
	s_add_i32 s91, s91, 1
	s_mov_b32 s68, s76
	s_cmp_lt_u32 s91, 8
	s_cselect_b64 s[4:5], -1, 0
	s_cbranch_scc0 .LBB0_227
	s_lshl_b32 s70, s91, 2
	s_lshr_b32 s70, 0x10765432, s70
	s_and_b32 s70, s70, 7
	s_lshl_b32 s70, s70, 2
	s_lshr_b32 s5, s2, 6
	s_or_b32 s70, s70, s5
	s_mov_b64 s[4:5], -1

.LBB0_561:
	s_add_i32 s48, s48, 1
	s_mov_b32 s18, s26
	s_cmp_lt_u32 s48, 4
	s_cselect_b64 s[4:5], -1, 0
	s_cbranch_scc0 .LBB0_567
	s_lshl_b32 s16, s48, 2
	s_lshr_b32 s5, s2, 6
	s_or_b32 s16, s16, s5
	s_mov_b64 s[4:5], -1
